# fp16 residual epilogues (out-proj, down): second 128-row half touched (one dword per line) while the first half's loads are in flight, so its real loads hit in L2
# baseline (speedup 1.0000x reference)
.LBB0_1254:
	s_andn2_b64 vcc, exec, s[54:55]
	s_cbranch_vccnz .LBB0_1256
	s_mov_b64 s[54:55], 0x80000
	v_ashrrev_i32_e32 v157, 31, v156
	v_lshl_add_u64 v[164:165], s[84:85], 0, v[158:159]
	v_lshlrev_b64 v[168:169], 12, v[156:157]
	v_lshl_add_u64 v[170:171], v[164:165], 0, v[168:169]
	v_lshl_add_u64 v[206:207], v[170:171], 0, s[54:55]
	global_load_dwordx2 v[186:187], v[170:171], off
	global_load_dwordx2 v[188:189], v[170:171], off offset:32
	global_load_dwordx2 v[198:199], v[170:171], off offset:256
	global_load_dwordx2 v[200:201], v[170:171], off offset:288
	global_load_dword v208, v[206:207], off
	global_load_dword v208, v[206:207], off offset:256
	v_lshlrev_b64 v[196:197], 12, v[166:167]
	v_lshl_add_u64 v[166:167], v[164:165], 0, v[196:197]
	v_lshl_add_u64 v[206:207], v[166:167], 0, s[54:55]
	global_load_dwordx2 v[204:205], v[166:167], off
	global_load_dwordx2 v[194:195], v[166:167], off offset:32
	global_load_dwordx2 v[192:193], v[166:167], off offset:256
	global_load_dwordx2 v[190:191], v[166:167], off offset:288
	global_load_dword v208, v[206:207], off
	global_load_dword v208, v[206:207], off offset:256
	v_lshlrev_b64 v[180:181], 12, v[162:163]
	v_lshl_add_u64 v[162:163], v[164:165], 0, v[180:181]
	v_lshl_add_u64 v[206:207], v[162:163], 0, s[54:55]
	global_load_dwordx2 v[182:183], v[162:163], off
	global_load_dwordx2 v[178:179], v[162:163], off offset:32
	global_load_dwordx2 v[176:177], v[162:163], off offset:256
	global_load_dwordx2 v[174:175], v[162:163], off offset:288
	global_load_dword v208, v[206:207], off
	global_load_dword v208, v[206:207], off offset:256
	v_lshlrev_b64 v[170:171], 12, v[160:161]
	v_lshl_add_u64 v[160:161], v[164:165], 0, v[170:171]
	v_lshl_add_u64 v[206:207], v[160:161], 0, s[54:55]
	global_load_dwordx2 v[172:173], v[160:161], off
	global_load_dwordx2 v[166:167], v[160:161], off offset:32
	global_load_dwordx2 v[162:163], v[160:161], off offset:256
	s_nop 0
	global_load_dwordx2 v[160:161], v[160:161], off offset:288
	global_load_dword v208, v[206:207], off
	global_load_dword v208, v[206:207], off offset:256
	v_lshl_add_u64 v[180:181], s[84:85], 0, v[180:181]
	v_lshl_add_u64 v[180:181], v[180:181], 0, v[158:159]
	v_lshl_add_u64 v[170:171], s[84:85], 0, v[170:171]
	v_lshl_add_u64 v[170:171], v[170:171], 0, v[158:159]
	s_waitcnt vmcnt(0)
	v_cvt_f32_f16_e32 v206, v187
	v_cvt_f32_f16_sdwa v207, v187 dst_sel:DWORD dst_unused:UNUSED_PAD src0_sel:WORD_1
	v_cvt_f32_f16_e32 v208, v186
	v_cvt_f32_f16_sdwa v209, v186 dst_sel:DWORD dst_unused:UNUSED_PAD src0_sel:WORD_1
	v_pk_fma_f32 v[206:207], v[130:131], v[146:147], v[206:207]
	s_nop 0
	v_cvt_pk_f16_f32 v207, v206, v207
	v_pk_fma_f32 v[186:187], v[128:129], v[144:145], v[208:209]
	v_lshl_add_u64 v[208:209], s[84:85], 0, v[168:169]
	v_lshl_add_u64 v[208:209], v[208:209], 0, v[158:159]
	v_cvt_pk_f16_f32 v206, v186, v187
	global_store_dwordx2 v[208:209], v[206:207], off
	v_cvt_f32_f16_e32 v186, v189
	v_cvt_f32_f16_sdwa v187, v189 dst_sel:DWORD dst_unused:UNUSED_PAD src0_sel:WORD_1
	v_cvt_f32_f16_e32 v206, v188
	v_cvt_f32_f16_sdwa v207, v188 dst_sel:DWORD dst_unused:UNUSED_PAD src0_sel:WORD_1
	v_pk_fma_f32 v[186:187], v[126:127], v[142:143], v[186:187]
	s_nop 0
	v_cvt_pk_f16_f32 v187, v186, v187
	v_pk_fma_f32 v[188:189], v[124:125], v[140:141], v[206:207]
	s_nop 0
	v_cvt_pk_f16_f32 v186, v188, v189
	global_store_dwordx2 v[208:209], v[186:187], off offset:32
	v_cvt_f32_f16_e32 v186, v199
	v_cvt_f32_f16_sdwa v187, v199 dst_sel:DWORD dst_unused:UNUSED_PAD src0_sel:WORD_1
	v_cvt_f32_f16_e32 v188, v198
	v_cvt_f32_f16_sdwa v189, v198 dst_sel:DWORD dst_unused:UNUSED_PAD src0_sel:WORD_1
	v_pk_fma_f32 v[186:187], v[98:99], v[138:139], v[186:187]
	s_nop 0
	v_cvt_pk_f16_f32 v187, v186, v187
	v_pk_fma_f32 v[188:189], v[96:97], v[136:137], v[188:189]
	s_nop 0
	v_cvt_pk_f16_f32 v186, v188, v189
	global_store_dwordx2 v[208:209], v[186:187], off offset:256
	v_cvt_f32_f16_e32 v186, v201
	v_cvt_f32_f16_sdwa v187, v201 dst_sel:DWORD dst_unused:UNUSED_PAD src0_sel:WORD_1
	v_cvt_f32_f16_e32 v188, v200
	v_cvt_f32_f16_sdwa v189, v200 dst_sel:DWORD dst_unused:UNUSED_PAD src0_sel:WORD_1
	v_pk_fma_f32 v[186:187], v[94:95], v[134:135], v[186:187]
	s_nop 0
	v_cvt_pk_f16_f32 v187, v186, v187
	v_pk_fma_f32 v[188:189], v[92:93], v[132:133], v[188:189]
	s_nop 0
	v_cvt_pk_f16_f32 v186, v188, v189
	global_store_dwordx2 v[208:209], v[186:187], off offset:288
	v_cvt_f32_f16_e32 v186, v205
	v_cvt_f32_f16_sdwa v187, v205 dst_sel:DWORD dst_unused:UNUSED_PAD src0_sel:WORD_1
	v_cvt_f32_f16_e32 v188, v204
	v_cvt_f32_f16_sdwa v189, v204 dst_sel:DWORD dst_unused:UNUSED_PAD src0_sel:WORD_1
	v_pk_fma_f32 v[200:201], v[122:123], v[146:147], v[186:187]
	v_lshl_add_u64 v[186:187], s[84:85], 0, v[196:197]
	v_pk_fma_f32 v[198:199], v[120:121], v[144:145], v[188:189]
	v_lshl_add_u64 v[196:197], v[186:187], 0, v[158:159]
	v_cvt_pk_f16_f32 v187, v200, v201
	v_cvt_pk_f16_f32 v186, v198, v199
	global_store_dwordx2 v[196:197], v[186:187], off
	v_cvt_f32_f16_e32 v186, v195
	v_cvt_f32_f16_sdwa v187, v195 dst_sel:DWORD dst_unused:UNUSED_PAD src0_sel:WORD_1
	v_cvt_f32_f16_e32 v188, v194
	v_cvt_f32_f16_sdwa v189, v194 dst_sel:DWORD dst_unused:UNUSED_PAD src0_sel:WORD_1
	v_pk_fma_f32 v[186:187], v[118:119], v[142:143], v[186:187]
	s_nop 0
	v_cvt_pk_f16_f32 v187, v186, v187
	v_pk_fma_f32 v[188:189], v[116:117], v[140:141], v[188:189]
	s_nop 0
	v_cvt_pk_f16_f32 v186, v188, v189
	global_store_dwordx2 v[196:197], v[186:187], off offset:32
	v_cvt_f32_f16_e32 v186, v193
	v_cvt_f32_f16_sdwa v187, v193 dst_sel:DWORD dst_unused:UNUSED_PAD src0_sel:WORD_1
	v_cvt_f32_f16_e32 v188, v192
	v_cvt_f32_f16_sdwa v189, v192 dst_sel:DWORD dst_unused:UNUSED_PAD src0_sel:WORD_1
	v_pk_fma_f32 v[186:187], v[90:91], v[138:139], v[186:187]
	s_nop 0
	v_cvt_pk_f16_f32 v187, v186, v187
	v_pk_fma_f32 v[188:189], v[88:89], v[136:137], v[188:189]
	s_nop 0
	v_cvt_pk_f16_f32 v186, v188, v189
	global_store_dwordx2 v[196:197], v[186:187], off offset:256
	v_cvt_f32_f16_e32 v186, v191
	v_cvt_f32_f16_sdwa v187, v191 dst_sel:DWORD dst_unused:UNUSED_PAD src0_sel:WORD_1
	v_cvt_f32_f16_e32 v188, v190
	v_cvt_f32_f16_sdwa v189, v190 dst_sel:DWORD dst_unused:UNUSED_PAD src0_sel:WORD_1
	v_pk_fma_f32 v[186:187], v[86:87], v[134:135], v[186:187]
	s_nop 0
	v_cvt_pk_f16_f32 v187, v186, v187
	v_pk_fma_f32 v[188:189], v[84:85], v[132:133], v[188:189]
	s_nop 0
	v_cvt_pk_f16_f32 v186, v188, v189
	global_store_dwordx2 v[196:197], v[186:187], off offset:288
	v_cvt_f32_f16_e32 v186, v183
	v_cvt_f32_f16_sdwa v187, v183 dst_sel:DWORD dst_unused:UNUSED_PAD src0_sel:WORD_1
	v_cvt_f32_f16_e32 v188, v182
	v_cvt_f32_f16_sdwa v189, v182 dst_sel:DWORD dst_unused:UNUSED_PAD src0_sel:WORD_1
	v_pk_fma_f32 v[186:187], v[114:115], v[146:147], v[186:187]
	s_nop 0
	v_cvt_pk_f16_f32 v187, v186, v187
	v_pk_fma_f32 v[182:183], v[112:113], v[144:145], v[188:189]
	s_nop 0
	v_cvt_pk_f16_f32 v186, v182, v183
	global_store_dwordx2 v[180:181], v[186:187], off
	v_cvt_f32_f16_e32 v182, v179
	v_cvt_f32_f16_sdwa v183, v179 dst_sel:DWORD dst_unused:UNUSED_PAD src0_sel:WORD_1
	v_cvt_f32_f16_e32 v186, v178
	v_cvt_f32_f16_sdwa v187, v178 dst_sel:DWORD dst_unused:UNUSED_PAD src0_sel:WORD_1
	v_pk_fma_f32 v[182:183], v[110:111], v[142:143], v[182:183]
	s_nop 0
	v_cvt_pk_f16_f32 v183, v182, v183
	v_pk_fma_f32 v[178:179], v[108:109], v[140:141], v[186:187]
	v_lshl_add_u64 v[186:187], v[168:169], 0, s[54:55]
	v_cvt_pk_f16_f32 v182, v178, v179
	global_store_dwordx2 v[180:181], v[182:183], off offset:32
	v_cvt_f32_f16_e32 v178, v177
	v_cvt_f32_f16_sdwa v179, v177 dst_sel:DWORD dst_unused:UNUSED_PAD src0_sel:WORD_1
	v_cvt_f32_f16_e32 v182, v176
	v_cvt_f32_f16_sdwa v183, v176 dst_sel:DWORD dst_unused:UNUSED_PAD src0_sel:WORD_1
	s_mov_b64 s[54:55], 0x90000
	v_pk_fma_f32 v[178:179], v[82:83], v[138:139], v[178:179]
	v_lshl_add_u64 v[196:197], v[168:169], 0, s[54:55]
	v_pk_fma_f32 v[176:177], v[80:81], v[136:137], v[182:183]
	v_cvt_pk_f16_f32 v179, v178, v179
	v_cvt_pk_f16_f32 v178, v176, v177
	global_store_dwordx2 v[180:181], v[178:179], off offset:256
	v_cvt_f32_f16_e32 v176, v175
	v_cvt_f32_f16_sdwa v177, v175 dst_sel:DWORD dst_unused:UNUSED_PAD src0_sel:WORD_1
	v_cvt_f32_f16_e32 v178, v174
	v_cvt_f32_f16_sdwa v179, v174 dst_sel:DWORD dst_unused:UNUSED_PAD src0_sel:WORD_1
	s_mov_b64 s[54:55], 0xa0000
	v_pk_fma_f32 v[176:177], v[78:79], v[134:135], v[176:177]
	v_pk_fma_f32 v[174:175], v[76:77], v[132:133], v[178:179]
	v_cvt_pk_f16_f32 v177, v176, v177
	v_cvt_pk_f16_f32 v176, v174, v175
	global_store_dwordx2 v[180:181], v[176:177], off offset:288
	v_cvt_f32_f16_e32 v174, v173
	v_cvt_f32_f16_sdwa v175, v173 dst_sel:DWORD dst_unused:UNUSED_PAD src0_sel:WORD_1
	v_cvt_f32_f16_e32 v176, v172
	v_cvt_f32_f16_sdwa v177, v172 dst_sel:DWORD dst_unused:UNUSED_PAD src0_sel:WORD_1
	v_pk_fma_f32 v[174:175], v[106:107], v[146:147], v[174:175]
	s_nop 0
	v_cvt_pk_f16_f32 v175, v174, v175
	v_pk_fma_f32 v[172:173], v[104:105], v[144:145], v[176:177]
	v_lshl_add_u64 v[176:177], v[168:169], 0, s[54:55]
	v_cvt_pk_f16_f32 v174, v172, v173
	global_store_dwordx2 v[170:171], v[174:175], off
	v_cvt_f32_f16_e32 v172, v167
	v_cvt_f32_f16_sdwa v173, v167 dst_sel:DWORD dst_unused:UNUSED_PAD src0_sel:WORD_1
	v_cvt_f32_f16_e32 v174, v166
	v_cvt_f32_f16_sdwa v175, v166 dst_sel:DWORD dst_unused:UNUSED_PAD src0_sel:WORD_1
	s_mov_b64 s[54:55], 0xb0000
	v_pk_fma_f32 v[172:173], v[102:103], v[142:143], v[172:173]
	v_pk_fma_f32 v[166:167], v[100:101], v[140:141], v[174:175]
	v_cvt_pk_f16_f32 v173, v172, v173
	v_cvt_pk_f16_f32 v172, v166, v167
	global_store_dwordx2 v[170:171], v[172:173], off offset:32
	v_cvt_f32_f16_e32 v166, v163
	v_cvt_f32_f16_sdwa v167, v163 dst_sel:DWORD dst_unused:UNUSED_PAD src0_sel:WORD_1
	v_cvt_f32_f16_e32 v172, v162
	v_cvt_f32_f16_sdwa v173, v162 dst_sel:DWORD dst_unused:UNUSED_PAD src0_sel:WORD_1
	v_pk_fma_f32 v[166:167], v[74:75], v[138:139], v[166:167]
	s_nop 0
	v_cvt_pk_f16_f32 v167, v166, v167
	v_pk_fma_f32 v[162:163], v[72:73], v[136:137], v[172:173]
	s_nop 0
	v_cvt_pk_f16_f32 v166, v162, v163
	global_store_dwordx2 v[170:171], v[166:167], off offset:256
	v_cvt_f32_f16_e32 v162, v161
	v_cvt_f32_f16_sdwa v163, v161 dst_sel:DWORD dst_unused:UNUSED_PAD src0_sel:WORD_1
	v_cvt_f32_f16_e32 v166, v160
	v_cvt_f32_f16_sdwa v167, v160 dst_sel:DWORD dst_unused:UNUSED_PAD src0_sel:WORD_1
	v_pk_fma_f32 v[162:163], v[70:71], v[134:135], v[162:163]
	s_nop 0
	v_cvt_pk_f16_f32 v163, v162, v163
	v_pk_fma_f32 v[160:161], v[68:69], v[132:133], v[166:167]
	v_lshl_add_u64 v[166:167], v[168:169], 0, s[54:55]
	v_cvt_pk_f16_f32 v162, v160, v161
	global_store_dwordx2 v[170:171], v[162:163], off offset:288
	v_lshl_add_u64 v[160:161], v[164:165], 0, v[186:187]
	global_load_dwordx2 v[188:189], v[160:161], off
	global_load_dwordx2 v[190:191], v[160:161], off offset:32
	global_load_dwordx2 v[192:193], v[160:161], off offset:256
	global_load_dwordx2 v[194:195], v[160:161], off offset:288
	v_lshl_add_u64 v[160:161], v[164:165], 0, v[196:197]
	global_load_dwordx2 v[198:199], v[160:161], off
	global_load_dwordx2 v[200:201], v[160:161], off offset:32
	global_load_dwordx2 v[182:183], v[160:161], off offset:256
	global_load_dwordx2 v[180:181], v[160:161], off offset:288
	v_lshl_add_u64 v[160:161], v[164:165], 0, v[176:177]
	global_load_dwordx2 v[178:179], v[160:161], off
	global_load_dwordx2 v[174:175], v[160:161], off offset:32
	global_load_dwordx2 v[172:173], v[160:161], off offset:256
	global_load_dwordx2 v[170:171], v[160:161], off offset:288
	v_lshl_add_u64 v[160:161], v[164:165], 0, v[166:167]
	global_load_dwordx2 v[168:169], v[160:161], off
	global_load_dwordx2 v[164:165], v[160:161], off offset:32
	global_load_dwordx2 v[162:163], v[160:161], off offset:256
	s_nop 0
	global_load_dwordx2 v[160:161], v[160:161], off offset:288
	v_lshl_add_u64 v[186:187], s[84:85], 0, v[186:187]
	v_lshl_add_u64 v[186:187], v[186:187], 0, v[158:159]
	v_lshl_add_u64 v[176:177], s[84:85], 0, v[176:177]
	v_lshl_add_u64 v[176:177], v[176:177], 0, v[158:159]
	v_lshl_add_u64 v[166:167], s[84:85], 0, v[166:167]
	s_waitcnt vmcnt(15)
	v_cvt_f32_f16_e32 v204, v189
	v_cvt_f32_f16_sdwa v205, v189 dst_sel:DWORD dst_unused:UNUSED_PAD src0_sel:WORD_1
	v_cvt_f32_f16_e32 v206, v188
	v_cvt_f32_f16_sdwa v207, v188 dst_sel:DWORD dst_unused:UNUSED_PAD src0_sel:WORD_1
	v_pk_fma_f32 v[204:205], v[66:67], v[146:147], v[204:205]
	s_nop 0
	v_cvt_pk_f16_f32 v205, v204, v205
	v_pk_fma_f32 v[188:189], v[64:65], v[144:145], v[206:207]
	s_nop 0
	v_cvt_pk_f16_f32 v204, v188, v189
	global_store_dwordx2 v[186:187], v[204:205], off
	s_waitcnt vmcnt(15)
	v_cvt_f32_f16_e32 v188, v191
	v_cvt_f32_f16_sdwa v189, v191 dst_sel:DWORD dst_unused:UNUSED_PAD src0_sel:WORD_1
	v_cvt_f32_f16_e32 v204, v190
	v_cvt_f32_f16_sdwa v205, v190 dst_sel:DWORD dst_unused:UNUSED_PAD src0_sel:WORD_1
	v_pk_fma_f32 v[188:189], v[62:63], v[142:143], v[188:189]
	s_nop 0
	v_cvt_pk_f16_f32 v189, v188, v189
	v_pk_fma_f32 v[190:191], v[60:61], v[140:141], v[204:205]
	s_nop 0
	v_cvt_pk_f16_f32 v188, v190, v191
	global_store_dwordx2 v[186:187], v[188:189], off offset:32
	s_waitcnt vmcnt(15)
	v_cvt_f32_f16_e32 v188, v193
	v_cvt_f32_f16_sdwa v189, v193 dst_sel:DWORD dst_unused:UNUSED_PAD src0_sel:WORD_1
	v_cvt_f32_f16_e32 v190, v192
	v_cvt_f32_f16_sdwa v191, v192 dst_sel:DWORD dst_unused:UNUSED_PAD src0_sel:WORD_1
	v_pk_fma_f32 v[188:189], v[32:33], v[138:139], v[188:189]
	s_nop 0
	v_cvt_pk_f16_f32 v189, v188, v189
	v_pk_fma_f32 v[190:191], v[30:31], v[136:137], v[190:191]
	s_nop 0
	v_cvt_pk_f16_f32 v188, v190, v191
	global_store_dwordx2 v[186:187], v[188:189], off offset:256
	s_waitcnt vmcnt(15)
	v_cvt_f32_f16_e32 v188, v195
	v_cvt_f32_f16_sdwa v189, v195 dst_sel:DWORD dst_unused:UNUSED_PAD src0_sel:WORD_1
	v_cvt_f32_f16_e32 v190, v194
	v_cvt_f32_f16_sdwa v191, v194 dst_sel:DWORD dst_unused:UNUSED_PAD src0_sel:WORD_1
	v_pk_fma_f32 v[188:189], v[28:29], v[134:135], v[188:189]
	s_nop 0
	v_cvt_pk_f16_f32 v189, v188, v189
	v_pk_fma_f32 v[190:191], v[26:27], v[132:133], v[190:191]
	s_nop 0
	v_cvt_pk_f16_f32 v188, v190, v191
	global_store_dwordx2 v[186:187], v[188:189], off offset:288
	s_waitcnt vmcnt(15)
	v_cvt_f32_f16_e32 v186, v199
	v_cvt_f32_f16_sdwa v187, v199 dst_sel:DWORD dst_unused:UNUSED_PAD src0_sel:WORD_1
	v_cvt_f32_f16_e32 v188, v198
	v_cvt_f32_f16_sdwa v189, v198 dst_sel:DWORD dst_unused:UNUSED_PAD src0_sel:WORD_1
	v_lshl_add_u64 v[190:191], s[84:85], 0, v[196:197]
	v_pk_fma_f32 v[186:187], v[58:59], v[146:147], v[186:187]
	v_lshl_add_u64 v[190:191], v[190:191], 0, v[158:159]
	v_pk_fma_f32 v[188:189], v[56:57], v[144:145], v[188:189]
	v_cvt_pk_f16_f32 v187, v186, v187
	v_cvt_pk_f16_f32 v186, v188, v189
	global_store_dwordx2 v[190:191], v[186:187], off
	s_waitcnt vmcnt(15)
	v_cvt_f32_f16_e32 v186, v201
	v_cvt_f32_f16_sdwa v187, v201 dst_sel:DWORD dst_unused:UNUSED_PAD src0_sel:WORD_1
	v_cvt_f32_f16_e32 v188, v200
	v_cvt_f32_f16_sdwa v189, v200 dst_sel:DWORD dst_unused:UNUSED_PAD src0_sel:WORD_1
	v_lshl_add_u64 v[158:159], v[166:167], 0, v[158:159]
	v_pk_fma_f32 v[186:187], v[54:55], v[142:143], v[186:187]
	v_pk_fma_f32 v[188:189], v[52:53], v[140:141], v[188:189]
	v_cvt_pk_f16_f32 v187, v186, v187
	v_cvt_pk_f16_f32 v186, v188, v189
	global_store_dwordx2 v[190:191], v[186:187], off offset:32
	s_waitcnt vmcnt(15)
	v_cvt_f32_f16_e32 v186, v183
	v_cvt_f32_f16_sdwa v187, v183 dst_sel:DWORD dst_unused:UNUSED_PAD src0_sel:WORD_1
	v_cvt_f32_f16_e32 v188, v182
	v_cvt_f32_f16_sdwa v189, v182 dst_sel:DWORD dst_unused:UNUSED_PAD src0_sel:WORD_1
	v_pk_fma_f32 v[186:187], v[24:25], v[138:139], v[186:187]
	s_nop 0
	v_cvt_pk_f16_f32 v187, v186, v187
	v_pk_fma_f32 v[182:183], v[22:23], v[136:137], v[188:189]
	s_nop 0
	v_cvt_pk_f16_f32 v186, v182, v183
	global_store_dwordx2 v[190:191], v[186:187], off offset:256
	s_waitcnt vmcnt(15)
	v_cvt_f32_f16_e32 v182, v181
	v_cvt_f32_f16_sdwa v183, v181 dst_sel:DWORD dst_unused:UNUSED_PAD src0_sel:WORD_1
	v_cvt_f32_f16_e32 v186, v180
	v_cvt_f32_f16_sdwa v187, v180 dst_sel:DWORD dst_unused:UNUSED_PAD src0_sel:WORD_1
	v_pk_fma_f32 v[182:183], v[20:21], v[134:135], v[182:183]
	s_nop 0
	v_cvt_pk_f16_f32 v183, v182, v183
	v_pk_fma_f32 v[180:181], v[18:19], v[132:133], v[186:187]
	s_nop 0
	v_cvt_pk_f16_f32 v182, v180, v181
	global_store_dwordx2 v[190:191], v[182:183], off offset:288
	s_waitcnt vmcnt(15)
	v_cvt_f32_f16_e32 v180, v179
	v_cvt_f32_f16_sdwa v181, v179 dst_sel:DWORD dst_unused:UNUSED_PAD src0_sel:WORD_1
	v_cvt_f32_f16_e32 v182, v178
	v_cvt_f32_f16_sdwa v183, v178 dst_sel:DWORD dst_unused:UNUSED_PAD src0_sel:WORD_1
	v_pk_fma_f32 v[180:181], v[50:51], v[146:147], v[180:181]
	s_nop 0
	v_cvt_pk_f16_f32 v181, v180, v181
	v_pk_fma_f32 v[178:179], v[48:49], v[144:145], v[182:183]
	s_nop 0
	v_cvt_pk_f16_f32 v180, v178, v179
	global_store_dwordx2 v[176:177], v[180:181], off
	s_waitcnt vmcnt(15)
	v_cvt_f32_f16_e32 v178, v175
	v_cvt_f32_f16_sdwa v179, v175 dst_sel:DWORD dst_unused:UNUSED_PAD src0_sel:WORD_1
	v_cvt_f32_f16_e32 v180, v174
	v_cvt_f32_f16_sdwa v181, v174 dst_sel:DWORD dst_unused:UNUSED_PAD src0_sel:WORD_1
	v_pk_fma_f32 v[178:179], v[46:47], v[142:143], v[178:179]
	s_nop 0
	v_cvt_pk_f16_f32 v179, v178, v179
	v_pk_fma_f32 v[174:175], v[44:45], v[140:141], v[180:181]
	s_nop 0
	v_cvt_pk_f16_f32 v178, v174, v175
	global_store_dwordx2 v[176:177], v[178:179], off offset:32
	s_waitcnt vmcnt(15)
	v_cvt_f32_f16_e32 v174, v173
	v_cvt_f32_f16_sdwa v175, v173 dst_sel:DWORD dst_unused:UNUSED_PAD src0_sel:WORD_1
	v_cvt_f32_f16_e32 v178, v172
	v_cvt_f32_f16_sdwa v179, v172 dst_sel:DWORD dst_unused:UNUSED_PAD src0_sel:WORD_1
	v_pk_fma_f32 v[174:175], v[16:17], v[138:139], v[174:175]
	s_nop 0
	v_cvt_pk_f16_f32 v175, v174, v175
	v_pk_fma_f32 v[172:173], v[14:15], v[136:137], v[178:179]
	s_nop 0
	v_cvt_pk_f16_f32 v174, v172, v173
	global_store_dwordx2 v[176:177], v[174:175], off offset:256
	s_waitcnt vmcnt(15)
	v_cvt_f32_f16_e32 v172, v171
	v_cvt_f32_f16_sdwa v173, v171 dst_sel:DWORD dst_unused:UNUSED_PAD src0_sel:WORD_1
	v_cvt_f32_f16_e32 v174, v170
	v_cvt_f32_f16_sdwa v175, v170 dst_sel:DWORD dst_unused:UNUSED_PAD src0_sel:WORD_1
	v_pk_fma_f32 v[172:173], v[12:13], v[134:135], v[172:173]
	s_nop 0
	v_cvt_pk_f16_f32 v173, v172, v173
	v_pk_fma_f32 v[170:171], v[10:11], v[132:133], v[174:175]
	s_nop 0
	v_cvt_pk_f16_f32 v172, v170, v171
	global_store_dwordx2 v[176:177], v[172:173], off offset:288
	s_waitcnt vmcnt(15)
	v_cvt_f32_f16_e32 v170, v169
	v_cvt_f32_f16_sdwa v171, v169 dst_sel:DWORD dst_unused:UNUSED_PAD src0_sel:WORD_1
	v_cvt_f32_f16_e32 v172, v168
	v_cvt_f32_f16_sdwa v173, v168 dst_sel:DWORD dst_unused:UNUSED_PAD src0_sel:WORD_1
	v_pk_fma_f32 v[146:147], v[42:43], v[146:147], v[170:171]
	s_nop 0
	v_cvt_pk_f16_f32 v147, v146, v147
	v_pk_fma_f32 v[144:145], v[40:41], v[144:145], v[172:173]
	s_nop 0
	v_cvt_pk_f16_f32 v146, v144, v145
	global_store_dwordx2 v[158:159], v[146:147], off
	s_waitcnt vmcnt(15)
	v_cvt_f32_f16_e32 v144, v165
	v_cvt_f32_f16_sdwa v145, v165 dst_sel:DWORD dst_unused:UNUSED_PAD src0_sel:WORD_1
	v_cvt_f32_f16_e32 v146, v164
	v_cvt_f32_f16_sdwa v147, v164 dst_sel:DWORD dst_unused:UNUSED_PAD src0_sel:WORD_1
	v_pk_fma_f32 v[142:143], v[38:39], v[142:143], v[144:145]
	s_nop 0
	v_cvt_pk_f16_f32 v143, v142, v143
	v_pk_fma_f32 v[140:141], v[36:37], v[140:141], v[146:147]
	s_nop 0
	v_cvt_pk_f16_f32 v142, v140, v141
	global_store_dwordx2 v[158:159], v[142:143], off offset:32
	s_waitcnt vmcnt(15)
	v_cvt_f32_f16_e32 v140, v163
	v_cvt_f32_f16_sdwa v141, v163 dst_sel:DWORD dst_unused:UNUSED_PAD src0_sel:WORD_1
	v_cvt_f32_f16_e32 v142, v162
	v_cvt_f32_f16_sdwa v143, v162 dst_sel:DWORD dst_unused:UNUSED_PAD src0_sel:WORD_1
	v_pk_fma_f32 v[138:139], v[8:9], v[138:139], v[140:141]
	s_nop 0
	v_cvt_pk_f16_f32 v139, v138, v139
	v_pk_fma_f32 v[136:137], v[6:7], v[136:137], v[142:143]
	s_nop 0
	v_cvt_pk_f16_f32 v138, v136, v137
	global_store_dwordx2 v[158:159], v[138:139], off offset:256
	s_waitcnt vmcnt(15)
	v_cvt_f32_f16_e32 v136, v161
	v_cvt_f32_f16_sdwa v137, v161 dst_sel:DWORD dst_unused:UNUSED_PAD src0_sel:WORD_1
	v_cvt_f32_f16_e32 v138, v160
	v_cvt_f32_f16_sdwa v139, v160 dst_sel:DWORD dst_unused:UNUSED_PAD src0_sel:WORD_1
	v_pk_fma_f32 v[134:135], v[4:5], v[134:135], v[136:137]
	s_nop 0
	v_cvt_pk_f16_f32 v135, v134, v135
	v_pk_fma_f32 v[132:133], v[2:3], v[132:133], v[138:139]
	s_nop 0
	v_cvt_pk_f16_f32 v134, v132, v133
	global_store_dwordx2 v[158:159], v[134:135], off offset:288

.LBB0_1580:
	v_lshl_add_u32 v156, s0, 8, v184
	v_lshl_or_b32 v154, s6, 8, v198
	s_mov_b64 s[50:51], -1
	s_cmp_lt_i32 s4, 0
	v_ashrrev_i32_e32 v155, 31, v154
	v_ashrrev_i32_e32 v157, 31, v156
	s_cbranch_scc0 .LBB0_1583
	s_mov_b64 s[50:51], 0x80000
	v_lshlrev_b64 v[158:159], 1, v[154:155]
	v_lshl_add_u64 v[160:161], s[84:85], 0, v[158:159]
	v_lshlrev_b64 v[162:163], 12, v[156:157]
	v_lshl_add_u64 v[132:133], v[154:155], 2, s[14:15]
	v_lshl_add_u64 v[164:165], v[160:161], 0, v[162:163]
	v_lshl_add_u64 v[206:207], v[164:165], 0, s[50:51]
	global_load_dwordx4 v[144:147], v[132:133], off
	global_load_dwordx4 v[140:143], v[132:133], off offset:64
	global_load_dwordx4 v[136:139], v[132:133], off offset:512
	s_nop 0
	global_load_dwordx4 v[132:135], v[132:133], off offset:576
	s_nop 0
	global_load_dwordx2 v[186:187], v[164:165], off
	global_load_dwordx2 v[188:189], v[164:165], off offset:32
	global_load_dwordx2 v[200:201], v[164:165], off offset:256
	global_load_dwordx2 v[202:203], v[164:165], off offset:288
	global_load_dword v208, v[206:207], off
	global_load_dword v208, v[206:207], off offset:256
	v_or_b32_e32 v164, 16, v156
	v_ashrrev_i32_e32 v165, 31, v164
	v_lshlrev_b64 v[196:197], 12, v[164:165]
	v_lshl_add_u64 v[164:165], v[160:161], 0, v[196:197]
	v_lshl_add_u64 v[206:207], v[164:165], 0, s[50:51]
	global_load_dwordx2 v[204:205], v[164:165], off
	global_load_dwordx2 v[194:195], v[164:165], off offset:32
	global_load_dwordx2 v[192:193], v[164:165], off offset:256
	global_load_dwordx2 v[190:191], v[164:165], off offset:288
	global_load_dword v208, v[206:207], off
	global_load_dword v208, v[206:207], off offset:256
	v_or_b32_e32 v164, 32, v156
	v_ashrrev_i32_e32 v165, 31, v164
	v_lshlrev_b64 v[180:181], 12, v[164:165]
	v_lshl_add_u64 v[164:165], v[160:161], 0, v[180:181]
	v_lshl_add_u64 v[206:207], v[164:165], 0, s[50:51]
	global_load_dwordx2 v[182:183], v[164:165], off
	global_load_dwordx2 v[178:179], v[164:165], off offset:32
	global_load_dwordx2 v[176:177], v[164:165], off offset:256
	global_load_dwordx2 v[172:173], v[164:165], off offset:288
	global_load_dword v208, v[206:207], off
	global_load_dword v208, v[206:207], off offset:256
	v_or_b32_e32 v164, 48, v156
	v_ashrrev_i32_e32 v165, 31, v164
	v_lshlrev_b64 v[170:171], 12, v[164:165]
	v_lshl_add_u64 v[164:165], v[160:161], 0, v[170:171]
	v_lshl_add_u64 v[206:207], v[164:165], 0, s[50:51]
	global_load_dwordx2 v[174:175], v[164:165], off
	global_load_dwordx2 v[168:169], v[164:165], off offset:32
	global_load_dwordx2 v[166:167], v[164:165], off offset:256
	s_nop 0
	global_load_dwordx2 v[164:165], v[164:165], off offset:288
	global_load_dword v208, v[206:207], off
	global_load_dword v208, v[206:207], off offset:256
	v_lshl_add_u64 v[196:197], s[84:85], 0, v[196:197]
	v_lshl_add_u64 v[196:197], v[196:197], 0, v[158:159]
	v_lshl_add_u64 v[180:181], s[84:85], 0, v[180:181]
	v_lshl_add_u64 v[180:181], v[180:181], 0, v[158:159]
	v_lshl_add_u64 v[170:171], s[84:85], 0, v[170:171]
	v_lshl_add_u64 v[170:171], v[170:171], 0, v[158:159]
	s_waitcnt vmcnt(0)
	v_cvt_f32_f16_e32 v206, v187
	v_cvt_f32_f16_sdwa v207, v187 dst_sel:DWORD dst_unused:UNUSED_PAD src0_sel:WORD_1
	v_cvt_f32_f16_e32 v208, v186
	v_cvt_f32_f16_sdwa v209, v186 dst_sel:DWORD dst_unused:UNUSED_PAD src0_sel:WORD_1
	v_pk_fma_f32 v[206:207], v[130:131], v[146:147], v[206:207]
	s_nop 0
	v_cvt_pk_f16_f32 v207, v206, v207
	v_pk_fma_f32 v[186:187], v[128:129], v[144:145], v[208:209]
	v_lshl_add_u64 v[208:209], s[84:85], 0, v[162:163]
	v_lshl_add_u64 v[208:209], v[208:209], 0, v[158:159]
	v_cvt_pk_f16_f32 v206, v186, v187
	global_store_dwordx2 v[208:209], v[206:207], off
	v_cvt_f32_f16_e32 v186, v189
	v_cvt_f32_f16_sdwa v187, v189 dst_sel:DWORD dst_unused:UNUSED_PAD src0_sel:WORD_1
	v_cvt_f32_f16_e32 v206, v188
	v_cvt_f32_f16_sdwa v207, v188 dst_sel:DWORD dst_unused:UNUSED_PAD src0_sel:WORD_1
	v_pk_fma_f32 v[186:187], v[126:127], v[142:143], v[186:187]
	s_nop 0
	v_cvt_pk_f16_f32 v187, v186, v187
	v_pk_fma_f32 v[188:189], v[124:125], v[140:141], v[206:207]
	s_nop 0
	v_cvt_pk_f16_f32 v186, v188, v189
	global_store_dwordx2 v[208:209], v[186:187], off offset:32
	v_cvt_f32_f16_e32 v186, v201
	v_cvt_f32_f16_sdwa v187, v201 dst_sel:DWORD dst_unused:UNUSED_PAD src0_sel:WORD_1
	v_cvt_f32_f16_e32 v188, v200
	v_cvt_f32_f16_sdwa v189, v200 dst_sel:DWORD dst_unused:UNUSED_PAD src0_sel:WORD_1
	v_pk_fma_f32 v[186:187], v[98:99], v[138:139], v[186:187]
	s_nop 0
	v_cvt_pk_f16_f32 v187, v186, v187
	v_pk_fma_f32 v[188:189], v[96:97], v[136:137], v[188:189]
	s_nop 0
	v_cvt_pk_f16_f32 v186, v188, v189
	global_store_dwordx2 v[208:209], v[186:187], off offset:256
	v_cvt_f32_f16_e32 v186, v203
	v_cvt_f32_f16_sdwa v187, v203 dst_sel:DWORD dst_unused:UNUSED_PAD src0_sel:WORD_1
	v_cvt_f32_f16_e32 v188, v202
	v_cvt_f32_f16_sdwa v189, v202 dst_sel:DWORD dst_unused:UNUSED_PAD src0_sel:WORD_1
	v_pk_fma_f32 v[186:187], v[94:95], v[134:135], v[186:187]
	s_nop 0
	v_cvt_pk_f16_f32 v187, v186, v187
	v_pk_fma_f32 v[188:189], v[92:93], v[132:133], v[188:189]
	s_nop 0
	v_cvt_pk_f16_f32 v186, v188, v189
	global_store_dwordx2 v[208:209], v[186:187], off offset:288
	v_cvt_f32_f16_e32 v186, v205
	v_cvt_f32_f16_sdwa v187, v205 dst_sel:DWORD dst_unused:UNUSED_PAD src0_sel:WORD_1
	v_cvt_f32_f16_e32 v188, v204
	v_cvt_f32_f16_sdwa v189, v204 dst_sel:DWORD dst_unused:UNUSED_PAD src0_sel:WORD_1
	v_pk_fma_f32 v[186:187], v[122:123], v[146:147], v[186:187]
	s_nop 0
	v_cvt_pk_f16_f32 v187, v186, v187
	v_pk_fma_f32 v[188:189], v[120:121], v[144:145], v[188:189]
	s_nop 0
	v_cvt_pk_f16_f32 v186, v188, v189
	global_store_dwordx2 v[196:197], v[186:187], off
	v_cvt_f32_f16_e32 v186, v195
	v_cvt_f32_f16_sdwa v187, v195 dst_sel:DWORD dst_unused:UNUSED_PAD src0_sel:WORD_1
	v_cvt_f32_f16_e32 v188, v194
	v_cvt_f32_f16_sdwa v189, v194 dst_sel:DWORD dst_unused:UNUSED_PAD src0_sel:WORD_1
	v_pk_fma_f32 v[186:187], v[118:119], v[142:143], v[186:187]
	s_nop 0
	v_cvt_pk_f16_f32 v187, v186, v187
	v_pk_fma_f32 v[188:189], v[116:117], v[140:141], v[188:189]
	s_nop 0
	v_cvt_pk_f16_f32 v186, v188, v189
	global_store_dwordx2 v[196:197], v[186:187], off offset:32
	v_cvt_f32_f16_e32 v186, v193
	v_cvt_f32_f16_sdwa v187, v193 dst_sel:DWORD dst_unused:UNUSED_PAD src0_sel:WORD_1
	v_cvt_f32_f16_e32 v188, v192
	v_cvt_f32_f16_sdwa v189, v192 dst_sel:DWORD dst_unused:UNUSED_PAD src0_sel:WORD_1
	v_pk_fma_f32 v[186:187], v[90:91], v[138:139], v[186:187]
	s_nop 0
	v_cvt_pk_f16_f32 v187, v186, v187
	v_pk_fma_f32 v[188:189], v[88:89], v[136:137], v[188:189]
	s_nop 0
	v_cvt_pk_f16_f32 v186, v188, v189
	global_store_dwordx2 v[196:197], v[186:187], off offset:256
	v_cvt_f32_f16_e32 v186, v191
	v_cvt_f32_f16_sdwa v187, v191 dst_sel:DWORD dst_unused:UNUSED_PAD src0_sel:WORD_1
	v_cvt_f32_f16_e32 v188, v190
	v_cvt_f32_f16_sdwa v189, v190 dst_sel:DWORD dst_unused:UNUSED_PAD src0_sel:WORD_1
	v_pk_fma_f32 v[186:187], v[86:87], v[134:135], v[186:187]
	s_nop 0
	v_cvt_pk_f16_f32 v187, v186, v187
	v_pk_fma_f32 v[188:189], v[84:85], v[132:133], v[188:189]
	s_nop 0
	v_cvt_pk_f16_f32 v186, v188, v189
	global_store_dwordx2 v[196:197], v[186:187], off offset:288
	v_cvt_f32_f16_e32 v186, v183
	v_cvt_f32_f16_sdwa v187, v183 dst_sel:DWORD dst_unused:UNUSED_PAD src0_sel:WORD_1
	v_cvt_f32_f16_e32 v188, v182
	v_cvt_f32_f16_sdwa v189, v182 dst_sel:DWORD dst_unused:UNUSED_PAD src0_sel:WORD_1
	v_pk_fma_f32 v[186:187], v[114:115], v[146:147], v[186:187]
	s_nop 0
	v_cvt_pk_f16_f32 v187, v186, v187
	v_pk_fma_f32 v[182:183], v[112:113], v[144:145], v[188:189]
	s_nop 0
	v_cvt_pk_f16_f32 v186, v182, v183
	global_store_dwordx2 v[180:181], v[186:187], off
	v_cvt_f32_f16_e32 v182, v179
	v_cvt_f32_f16_sdwa v183, v179 dst_sel:DWORD dst_unused:UNUSED_PAD src0_sel:WORD_1
	v_cvt_f32_f16_e32 v186, v178
	v_cvt_f32_f16_sdwa v187, v178 dst_sel:DWORD dst_unused:UNUSED_PAD src0_sel:WORD_1
	v_pk_fma_f32 v[182:183], v[110:111], v[142:143], v[182:183]
	s_nop 0
	v_cvt_pk_f16_f32 v183, v182, v183
	v_pk_fma_f32 v[178:179], v[108:109], v[140:141], v[186:187]
	v_lshl_add_u64 v[186:187], v[162:163], 0, s[50:51]
	v_cvt_pk_f16_f32 v182, v178, v179
	global_store_dwordx2 v[180:181], v[182:183], off offset:32
	v_cvt_f32_f16_e32 v178, v177
	v_cvt_f32_f16_sdwa v179, v177 dst_sel:DWORD dst_unused:UNUSED_PAD src0_sel:WORD_1
	v_cvt_f32_f16_e32 v182, v176
	v_cvt_f32_f16_sdwa v183, v176 dst_sel:DWORD dst_unused:UNUSED_PAD src0_sel:WORD_1
	s_mov_b64 s[50:51], 0x90000
	v_pk_fma_f32 v[178:179], v[82:83], v[138:139], v[178:179]
	v_lshl_add_u64 v[196:197], v[162:163], 0, s[50:51]
	v_pk_fma_f32 v[176:177], v[80:81], v[136:137], v[182:183]
	v_cvt_pk_f16_f32 v179, v178, v179
	v_cvt_pk_f16_f32 v178, v176, v177
	global_store_dwordx2 v[180:181], v[178:179], off offset:256
	v_cvt_f32_f16_e32 v176, v173
	v_cvt_f32_f16_sdwa v177, v173 dst_sel:DWORD dst_unused:UNUSED_PAD src0_sel:WORD_1
	v_cvt_f32_f16_e32 v178, v172
	v_cvt_f32_f16_sdwa v179, v172 dst_sel:DWORD dst_unused:UNUSED_PAD src0_sel:WORD_1
	s_mov_b64 s[50:51], 0xa0000
	v_pk_fma_f32 v[176:177], v[78:79], v[134:135], v[176:177]
	v_pk_fma_f32 v[172:173], v[76:77], v[132:133], v[178:179]
	v_cvt_pk_f16_f32 v177, v176, v177
	v_cvt_pk_f16_f32 v176, v172, v173
	global_store_dwordx2 v[180:181], v[176:177], off offset:288
	v_cvt_f32_f16_e32 v172, v175
	v_cvt_f32_f16_sdwa v173, v175 dst_sel:DWORD dst_unused:UNUSED_PAD src0_sel:WORD_1
	v_cvt_f32_f16_e32 v176, v174
	v_cvt_f32_f16_sdwa v177, v174 dst_sel:DWORD dst_unused:UNUSED_PAD src0_sel:WORD_1
	v_pk_fma_f32 v[172:173], v[106:107], v[146:147], v[172:173]
	s_nop 0
	v_cvt_pk_f16_f32 v173, v172, v173
	v_pk_fma_f32 v[174:175], v[104:105], v[144:145], v[176:177]
	v_lshl_add_u64 v[176:177], v[162:163], 0, s[50:51]
	v_cvt_pk_f16_f32 v172, v174, v175
	global_store_dwordx2 v[170:171], v[172:173], off
	v_cvt_f32_f16_e32 v172, v169
	v_cvt_f32_f16_sdwa v173, v169 dst_sel:DWORD dst_unused:UNUSED_PAD src0_sel:WORD_1
	v_cvt_f32_f16_e32 v174, v168
	v_cvt_f32_f16_sdwa v175, v168 dst_sel:DWORD dst_unused:UNUSED_PAD src0_sel:WORD_1
	s_mov_b64 s[50:51], 0xb0000
	v_pk_fma_f32 v[172:173], v[102:103], v[142:143], v[172:173]
	v_pk_fma_f32 v[168:169], v[100:101], v[140:141], v[174:175]
	v_cvt_pk_f16_f32 v173, v172, v173
	v_cvt_pk_f16_f32 v172, v168, v169
	global_store_dwordx2 v[170:171], v[172:173], off offset:32
	v_cvt_f32_f16_e32 v168, v167
	v_cvt_f32_f16_sdwa v169, v167 dst_sel:DWORD dst_unused:UNUSED_PAD src0_sel:WORD_1
	v_cvt_f32_f16_e32 v172, v166
	v_cvt_f32_f16_sdwa v173, v166 dst_sel:DWORD dst_unused:UNUSED_PAD src0_sel:WORD_1
	v_pk_fma_f32 v[168:169], v[74:75], v[138:139], v[168:169]
	s_nop 0
	v_cvt_pk_f16_f32 v169, v168, v169
	v_pk_fma_f32 v[166:167], v[72:73], v[136:137], v[172:173]
	s_nop 0
	v_cvt_pk_f16_f32 v168, v166, v167
	global_store_dwordx2 v[170:171], v[168:169], off offset:256
	v_cvt_f32_f16_e32 v166, v165
	v_cvt_f32_f16_sdwa v167, v165 dst_sel:DWORD dst_unused:UNUSED_PAD src0_sel:WORD_1
	v_cvt_f32_f16_e32 v168, v164
	v_cvt_f32_f16_sdwa v169, v164 dst_sel:DWORD dst_unused:UNUSED_PAD src0_sel:WORD_1
	v_pk_fma_f32 v[166:167], v[70:71], v[134:135], v[166:167]
	s_nop 0
	v_cvt_pk_f16_f32 v167, v166, v167
	v_pk_fma_f32 v[164:165], v[68:69], v[132:133], v[168:169]
	s_nop 0
	v_cvt_pk_f16_f32 v166, v164, v165
	global_store_dwordx2 v[170:171], v[166:167], off offset:288
	v_lshl_add_u64 v[164:165], v[160:161], 0, v[186:187]
	global_load_dwordx2 v[188:189], v[164:165], off
	global_load_dwordx2 v[190:191], v[164:165], off offset:32
	global_load_dwordx2 v[192:193], v[164:165], off offset:256
	global_load_dwordx2 v[194:195], v[164:165], off offset:288
	v_lshl_add_u64 v[164:165], v[160:161], 0, v[196:197]
	global_load_dwordx2 v[200:201], v[164:165], off
	global_load_dwordx2 v[202:203], v[164:165], off offset:32
	global_load_dwordx2 v[182:183], v[164:165], off offset:256
	global_load_dwordx2 v[180:181], v[164:165], off offset:288
	v_lshl_add_u64 v[164:165], v[160:161], 0, v[176:177]
	global_load_dwordx2 v[178:179], v[164:165], off
	global_load_dwordx2 v[174:175], v[164:165], off offset:32
	global_load_dwordx2 v[172:173], v[164:165], off offset:256
	global_load_dwordx2 v[170:171], v[164:165], off offset:288
	v_lshl_add_u64 v[166:167], v[162:163], 0, s[50:51]
	v_lshl_add_u64 v[160:161], v[160:161], 0, v[166:167]
	global_load_dwordx2 v[168:169], v[160:161], off
	global_load_dwordx2 v[164:165], v[160:161], off offset:32
	global_load_dwordx2 v[162:163], v[160:161], off offset:256
	s_nop 0
	global_load_dwordx2 v[160:161], v[160:161], off offset:288
	v_lshl_add_u64 v[186:187], s[84:85], 0, v[186:187]
	v_lshl_add_u64 v[186:187], v[186:187], 0, v[158:159]
	v_lshl_add_u64 v[176:177], s[84:85], 0, v[176:177]
	v_lshl_add_u64 v[176:177], v[176:177], 0, v[158:159]
	v_lshl_add_u64 v[166:167], s[84:85], 0, v[166:167]
	s_waitcnt vmcnt(15)
	v_cvt_f32_f16_e32 v204, v189
	v_cvt_f32_f16_sdwa v205, v189 dst_sel:DWORD dst_unused:UNUSED_PAD src0_sel:WORD_1
	v_cvt_f32_f16_e32 v206, v188
	v_cvt_f32_f16_sdwa v207, v188 dst_sel:DWORD dst_unused:UNUSED_PAD src0_sel:WORD_1
	v_pk_fma_f32 v[204:205], v[66:67], v[146:147], v[204:205]
	s_nop 0
	v_cvt_pk_f16_f32 v205, v204, v205
	v_pk_fma_f32 v[188:189], v[64:65], v[144:145], v[206:207]
	s_nop 0
	v_cvt_pk_f16_f32 v204, v188, v189
	global_store_dwordx2 v[186:187], v[204:205], off
	s_waitcnt vmcnt(15)
	v_cvt_f32_f16_e32 v188, v191
	v_cvt_f32_f16_sdwa v189, v191 dst_sel:DWORD dst_unused:UNUSED_PAD src0_sel:WORD_1
	v_cvt_f32_f16_e32 v204, v190
	v_cvt_f32_f16_sdwa v205, v190 dst_sel:DWORD dst_unused:UNUSED_PAD src0_sel:WORD_1
	v_pk_fma_f32 v[188:189], v[62:63], v[142:143], v[188:189]
	s_nop 0
	v_cvt_pk_f16_f32 v189, v188, v189
	v_pk_fma_f32 v[190:191], v[60:61], v[140:141], v[204:205]
	s_nop 0
	v_cvt_pk_f16_f32 v188, v190, v191
	global_store_dwordx2 v[186:187], v[188:189], off offset:32
	s_waitcnt vmcnt(15)
	v_cvt_f32_f16_e32 v188, v193
	v_cvt_f32_f16_sdwa v189, v193 dst_sel:DWORD dst_unused:UNUSED_PAD src0_sel:WORD_1
	v_cvt_f32_f16_e32 v190, v192
	v_cvt_f32_f16_sdwa v191, v192 dst_sel:DWORD dst_unused:UNUSED_PAD src0_sel:WORD_1
	v_pk_fma_f32 v[188:189], v[32:33], v[138:139], v[188:189]
	s_nop 0
	v_cvt_pk_f16_f32 v189, v188, v189
	v_pk_fma_f32 v[190:191], v[30:31], v[136:137], v[190:191]
	s_nop 0
	v_cvt_pk_f16_f32 v188, v190, v191
	global_store_dwordx2 v[186:187], v[188:189], off offset:256
	s_waitcnt vmcnt(15)
	v_cvt_f32_f16_e32 v188, v195
	v_cvt_f32_f16_sdwa v189, v195 dst_sel:DWORD dst_unused:UNUSED_PAD src0_sel:WORD_1
	v_cvt_f32_f16_e32 v190, v194
	v_cvt_f32_f16_sdwa v191, v194 dst_sel:DWORD dst_unused:UNUSED_PAD src0_sel:WORD_1
	v_pk_fma_f32 v[188:189], v[28:29], v[134:135], v[188:189]
	s_nop 0
	v_cvt_pk_f16_f32 v189, v188, v189
	v_pk_fma_f32 v[190:191], v[26:27], v[132:133], v[190:191]
	s_nop 0
	v_cvt_pk_f16_f32 v188, v190, v191
	global_store_dwordx2 v[186:187], v[188:189], off offset:288
	s_waitcnt vmcnt(15)
	v_cvt_f32_f16_e32 v186, v201
	v_cvt_f32_f16_sdwa v187, v201 dst_sel:DWORD dst_unused:UNUSED_PAD src0_sel:WORD_1
	v_cvt_f32_f16_e32 v188, v200
	v_cvt_f32_f16_sdwa v189, v200 dst_sel:DWORD dst_unused:UNUSED_PAD src0_sel:WORD_1
	v_lshl_add_u64 v[190:191], s[84:85], 0, v[196:197]
	v_pk_fma_f32 v[186:187], v[58:59], v[146:147], v[186:187]
	v_lshl_add_u64 v[190:191], v[190:191], 0, v[158:159]
	v_pk_fma_f32 v[188:189], v[56:57], v[144:145], v[188:189]
	v_cvt_pk_f16_f32 v187, v186, v187
	v_cvt_pk_f16_f32 v186, v188, v189
	global_store_dwordx2 v[190:191], v[186:187], off
	s_waitcnt vmcnt(15)
	v_cvt_f32_f16_e32 v186, v203
	v_cvt_f32_f16_sdwa v187, v203 dst_sel:DWORD dst_unused:UNUSED_PAD src0_sel:WORD_1
	v_cvt_f32_f16_e32 v188, v202
	v_cvt_f32_f16_sdwa v189, v202 dst_sel:DWORD dst_unused:UNUSED_PAD src0_sel:WORD_1
	v_lshl_add_u64 v[158:159], v[166:167], 0, v[158:159]
	v_pk_fma_f32 v[186:187], v[54:55], v[142:143], v[186:187]
	v_pk_fma_f32 v[188:189], v[52:53], v[140:141], v[188:189]
	v_cvt_pk_f16_f32 v187, v186, v187
	v_cvt_pk_f16_f32 v186, v188, v189
	global_store_dwordx2 v[190:191], v[186:187], off offset:32
	s_waitcnt vmcnt(15)
	v_cvt_f32_f16_e32 v186, v183
	v_cvt_f32_f16_sdwa v187, v183 dst_sel:DWORD dst_unused:UNUSED_PAD src0_sel:WORD_1
	v_cvt_f32_f16_e32 v188, v182
	v_cvt_f32_f16_sdwa v189, v182 dst_sel:DWORD dst_unused:UNUSED_PAD src0_sel:WORD_1
	v_pk_fma_f32 v[186:187], v[24:25], v[138:139], v[186:187]
	s_nop 0
	v_cvt_pk_f16_f32 v187, v186, v187
	v_pk_fma_f32 v[182:183], v[22:23], v[136:137], v[188:189]
	s_nop 0
	v_cvt_pk_f16_f32 v186, v182, v183
	global_store_dwordx2 v[190:191], v[186:187], off offset:256
	s_waitcnt vmcnt(15)
	v_cvt_f32_f16_e32 v182, v181
	v_cvt_f32_f16_sdwa v183, v181 dst_sel:DWORD dst_unused:UNUSED_PAD src0_sel:WORD_1
	v_cvt_f32_f16_e32 v186, v180
	v_cvt_f32_f16_sdwa v187, v180 dst_sel:DWORD dst_unused:UNUSED_PAD src0_sel:WORD_1
	v_pk_fma_f32 v[182:183], v[20:21], v[134:135], v[182:183]
	s_nop 0
	v_cvt_pk_f16_f32 v183, v182, v183
	v_pk_fma_f32 v[180:181], v[18:19], v[132:133], v[186:187]
	s_nop 0
	v_cvt_pk_f16_f32 v182, v180, v181
	global_store_dwordx2 v[190:191], v[182:183], off offset:288
	s_waitcnt vmcnt(15)
	v_cvt_f32_f16_e32 v180, v179
	v_cvt_f32_f16_sdwa v181, v179 dst_sel:DWORD dst_unused:UNUSED_PAD src0_sel:WORD_1
	v_cvt_f32_f16_e32 v182, v178
	v_cvt_f32_f16_sdwa v183, v178 dst_sel:DWORD dst_unused:UNUSED_PAD src0_sel:WORD_1
	v_pk_fma_f32 v[180:181], v[50:51], v[146:147], v[180:181]
	s_nop 0
	v_cvt_pk_f16_f32 v181, v180, v181
	v_pk_fma_f32 v[178:179], v[48:49], v[144:145], v[182:183]
	s_nop 0
	v_cvt_pk_f16_f32 v180, v178, v179
	global_store_dwordx2 v[176:177], v[180:181], off
	s_waitcnt vmcnt(15)
	v_cvt_f32_f16_e32 v178, v175
	v_cvt_f32_f16_sdwa v179, v175 dst_sel:DWORD dst_unused:UNUSED_PAD src0_sel:WORD_1
	v_cvt_f32_f16_e32 v180, v174
	v_cvt_f32_f16_sdwa v181, v174 dst_sel:DWORD dst_unused:UNUSED_PAD src0_sel:WORD_1
	v_pk_fma_f32 v[178:179], v[46:47], v[142:143], v[178:179]
	s_nop 0
	v_cvt_pk_f16_f32 v179, v178, v179
	v_pk_fma_f32 v[174:175], v[44:45], v[140:141], v[180:181]
	s_nop 0
	v_cvt_pk_f16_f32 v178, v174, v175
	global_store_dwordx2 v[176:177], v[178:179], off offset:32
	s_waitcnt vmcnt(15)
	v_cvt_f32_f16_e32 v174, v173
	v_cvt_f32_f16_sdwa v175, v173 dst_sel:DWORD dst_unused:UNUSED_PAD src0_sel:WORD_1
	v_cvt_f32_f16_e32 v178, v172
	v_cvt_f32_f16_sdwa v179, v172 dst_sel:DWORD dst_unused:UNUSED_PAD src0_sel:WORD_1
	v_pk_fma_f32 v[174:175], v[16:17], v[138:139], v[174:175]
	s_nop 0
	v_cvt_pk_f16_f32 v175, v174, v175
	v_pk_fma_f32 v[172:173], v[14:15], v[136:137], v[178:179]
	s_nop 0
	v_cvt_pk_f16_f32 v174, v172, v173
	global_store_dwordx2 v[176:177], v[174:175], off offset:256
	s_waitcnt vmcnt(15)
	v_cvt_f32_f16_e32 v172, v171
	v_cvt_f32_f16_sdwa v173, v171 dst_sel:DWORD dst_unused:UNUSED_PAD src0_sel:WORD_1
	v_cvt_f32_f16_e32 v174, v170
	v_cvt_f32_f16_sdwa v175, v170 dst_sel:DWORD dst_unused:UNUSED_PAD src0_sel:WORD_1
	v_pk_fma_f32 v[172:173], v[12:13], v[134:135], v[172:173]
	s_nop 0
	v_cvt_pk_f16_f32 v173, v172, v173
	v_pk_fma_f32 v[170:171], v[10:11], v[132:133], v[174:175]
	s_nop 0
	v_cvt_pk_f16_f32 v172, v170, v171
	global_store_dwordx2 v[176:177], v[172:173], off offset:288
	s_waitcnt vmcnt(15)
	v_cvt_f32_f16_e32 v170, v169
	v_cvt_f32_f16_sdwa v171, v169 dst_sel:DWORD dst_unused:UNUSED_PAD src0_sel:WORD_1
	v_cvt_f32_f16_e32 v172, v168
	v_cvt_f32_f16_sdwa v173, v168 dst_sel:DWORD dst_unused:UNUSED_PAD src0_sel:WORD_1
	v_pk_fma_f32 v[146:147], v[42:43], v[146:147], v[170:171]
	s_nop 0
	v_cvt_pk_f16_f32 v147, v146, v147
	v_pk_fma_f32 v[144:145], v[40:41], v[144:145], v[172:173]
	s_nop 0
	v_cvt_pk_f16_f32 v146, v144, v145
	global_store_dwordx2 v[158:159], v[146:147], off
	s_waitcnt vmcnt(15)
	v_cvt_f32_f16_e32 v144, v165
	v_cvt_f32_f16_sdwa v145, v165 dst_sel:DWORD dst_unused:UNUSED_PAD src0_sel:WORD_1
	v_cvt_f32_f16_e32 v146, v164
	v_cvt_f32_f16_sdwa v147, v164 dst_sel:DWORD dst_unused:UNUSED_PAD src0_sel:WORD_1
	v_pk_fma_f32 v[142:143], v[38:39], v[142:143], v[144:145]
	s_nop 0
	v_cvt_pk_f16_f32 v143, v142, v143
	v_pk_fma_f32 v[140:141], v[36:37], v[140:141], v[146:147]
	s_nop 0
	v_cvt_pk_f16_f32 v142, v140, v141
	global_store_dwordx2 v[158:159], v[142:143], off offset:32
	s_waitcnt vmcnt(15)
	v_cvt_f32_f16_e32 v140, v163
	v_cvt_f32_f16_sdwa v141, v163 dst_sel:DWORD dst_unused:UNUSED_PAD src0_sel:WORD_1
	v_cvt_f32_f16_e32 v142, v162
	v_cvt_f32_f16_sdwa v143, v162 dst_sel:DWORD dst_unused:UNUSED_PAD src0_sel:WORD_1
	v_pk_fma_f32 v[138:139], v[8:9], v[138:139], v[140:141]
	s_nop 0
	v_cvt_pk_f16_f32 v139, v138, v139
	v_pk_fma_f32 v[136:137], v[6:7], v[136:137], v[142:143]
	s_nop 0
	v_cvt_pk_f16_f32 v138, v136, v137
	global_store_dwordx2 v[158:159], v[138:139], off offset:256
	s_waitcnt vmcnt(15)
	v_cvt_f32_f16_e32 v136, v161
	v_cvt_f32_f16_sdwa v137, v161 dst_sel:DWORD dst_unused:UNUSED_PAD src0_sel:WORD_1
	v_cvt_f32_f16_e32 v138, v160
	v_cvt_f32_f16_sdwa v139, v160 dst_sel:DWORD dst_unused:UNUSED_PAD src0_sel:WORD_1
	v_pk_fma_f32 v[134:135], v[4:5], v[134:135], v[136:137]
	s_nop 0
	v_cvt_pk_f16_f32 v135, v134, v135
	v_pk_fma_f32 v[132:133], v[2:3], v[132:133], v[138:139]
	s_nop 0
	v_cvt_pk_f16_f32 v134, v132, v133
	global_store_dwordx2 v[158:159], v[134:135], off offset:288
	s_cbranch_execz .LBB0_1584
